# attention: second V fragment batch read at MFMA segment head, group-0 pair sums moved into first PV gap
# speedup vs baseline: 1.0052x; 1.0052x over previous
; __device__ __forceinline__ float fexp2(float x) { return __builtin_amdgcn_exp2f(x); }
; __device__ __forceinline__ float max3f(float a, float b, float c) { float r; asm("v_max3_f32 %0, %1, %2, %3" : "=v"(r) : "v"(a), "v"(b), "v"(c)); return r; }
; __device__ __forceinline__ void attn_phase(LAS unsigned char* lds, const bf16_t* Q, const bf16_t* Kimg, const bf16_t* Vimg, const bf16_t* Kmeta, const bf16_t* Vmeta,
;                                            bf16_t* O, const float* lamp, const float* sublnw, float lambda_init, int G) {
;     ...
;                     float mxa = max3f(sA[0], sA[1], sA[2]), mxb = max3f(sB[0], sB[1], sB[2]);
; #pragma unroll
;                     for (int r = 3; r < 15; r += 2) { mxa = max3f(mxa, sA[r], sA[r + 1]); mxb = max3f(mxb, sB[r], sB[r + 1]); }
;                     float mx = max3f(mxa, mxb, sA[15]); mx = fmaxf(mx, sB[15]);
;                     mx = half_max(mx);
;                     alpha = 1.f;
;                     if (__any(mx > 64.f)) { const float d = fmaxf(mx, 0.f); alpha = fexp2(-d); mrun += d;
; #pragma unroll
;                         for (int r = 0; r < 16; ++r) { sA[r] -= d; sB[r] -= d; } }
.LBB0_758:
	s_add_i32 s10, s38, 0x4000
	s_and_b32 s10, s10, 0xc000
	v_add_u32_e32 v234, s10, v220
	ds_read_b128 v[184:187], v234
	ds_read_b128 v[188:191], v234 offset:512
	ds_read_b128 v[202:205], v234 offset:1024
	ds_read_b128 v[246:249], v234 offset:1536
	v_max3_f32 v2, v18, v19, v20
	v_max3_f32 v3, v34, v35, v36
	v_max3_f32 v2, v2, v21, v22
	v_max3_f32 v3, v3, v37, v38
	v_max3_f32 v2, v2, v23, v24
	v_max3_f32 v3, v3, v39, v40
	v_max3_f32 v2, v2, v25, v26
	v_max3_f32 v3, v3, v41, v42
	v_max3_f32 v2, v2, v27, v28
	v_max3_f32 v3, v3, v43, v44
	v_max3_f32 v2, v2, v29, v30
	v_max3_f32 v3, v3, v45, v46
	v_max3_f32 v2, v2, v31, v32
	v_max3_f32 v3, v3, v47, v48
	v_max3_f32 v2, v2, v3, v33
	v_max_f32_e32 v2, v2, v49
	v_mov_b32_e32 v3, v2
	s_nop 1
	v_permlane32_swap_b32_e32 v2, v3
	v_max_f32_e32 v2, v2, v3
	v_cmp_lt_f32_e32 vcc, s45, v2
	s_cbranch_vccz .LBB0_760
	v_max_f32_e32 v2, v2, v2
	v_max_f32_e32 v2, 0, v2
	v_exp_f32_e64 v178, -v2
	v_pk_add_f32 v[18:19], v[18:19], v[2:3] op_sel_hi:[1,0] neg_lo:[0,1] neg_hi:[0,1]
	v_pk_add_f32 v[34:35], v[34:35], v[2:3] op_sel_hi:[1,0] neg_lo:[0,1] neg_hi:[0,1]
	v_pk_add_f32 v[20:21], v[20:21], v[2:3] op_sel_hi:[1,0] neg_lo:[0,1] neg_hi:[0,1]
	v_pk_add_f32 v[36:37], v[36:37], v[2:3] op_sel_hi:[1,0] neg_lo:[0,1] neg_hi:[0,1]
	v_pk_add_f32 v[22:23], v[22:23], v[2:3] op_sel_hi:[1,0] neg_lo:[0,1] neg_hi:[0,1]
	v_pk_add_f32 v[38:39], v[38:39], v[2:3] op_sel_hi:[1,0] neg_lo:[0,1] neg_hi:[0,1]
	v_pk_add_f32 v[24:25], v[24:25], v[2:3] op_sel_hi:[1,0] neg_lo:[0,1] neg_hi:[0,1]
	v_pk_add_f32 v[40:41], v[40:41], v[2:3] op_sel_hi:[1,0] neg_lo:[0,1] neg_hi:[0,1]
	v_pk_add_f32 v[26:27], v[26:27], v[2:3] op_sel_hi:[1,0] neg_lo:[0,1] neg_hi:[0,1]
	v_pk_add_f32 v[42:43], v[42:43], v[2:3] op_sel_hi:[1,0] neg_lo:[0,1] neg_hi:[0,1]
	v_pk_add_f32 v[28:29], v[28:29], v[2:3] op_sel_hi:[1,0] neg_lo:[0,1] neg_hi:[0,1]
	v_pk_add_f32 v[44:45], v[44:45], v[2:3] op_sel_hi:[1,0] neg_lo:[0,1] neg_hi:[0,1]
	v_pk_add_f32 v[30:31], v[30:31], v[2:3] op_sel_hi:[1,0] neg_lo:[0,1] neg_hi:[0,1]
	v_pk_add_f32 v[46:47], v[46:47], v[2:3] op_sel_hi:[1,0] neg_lo:[0,1] neg_hi:[0,1]
	v_pk_add_f32 v[32:33], v[32:33], v[2:3] op_sel_hi:[1,0] neg_lo:[0,1] neg_hi:[0,1]
	v_pk_add_f32 v[48:49], v[48:49], v[2:3] op_sel_hi:[1,0] neg_lo:[0,1] neg_hi:[0,1]
	v_add_f32_e32 v173, v173, v2
	s_branch .LBB0_761

; __device__ __forceinline__ unsigned pk_bf16(float lo, float hi) { f32x2_t v = {lo, hi}; bf16x2_t b = __builtin_convertvector(v, bf16x2_t); return __builtin_bit_cast(unsigned, b); }
; __device__ __forceinline__ float fexp2(float x) { return __builtin_amdgcn_exp2f(x); }
; __device__ __forceinline__ void attn_phase(LAS unsigned char* lds, const bf16_t* Q, const bf16_t* Kimg, const bf16_t* Vimg, const bf16_t* Kmeta, const bf16_t* Vmeta,
;                                            bf16_t* O, const float* lamp, const float* sublnw, float lambda_init, int G) {
;     ...
;                     float ps = 0.f;
; #pragma unroll
;                     for (int q4 = 0; q4 < 8; ++q4) {
;                         const float a0 = fexp2(sA[2 * q4]), a1 = fexp2(sA[2 * q4 + 1]), b0 = fexp2(sB[2 * q4]), b1 = fexp2(sB[2 * q4 + 1]);
;                         ps += (a0 + a1) + (b0 + b1);
;                         pk[q4 >> 2][q4 & 3] = pk_bf16(a0, a1); pk[2 + (q4 >> 2)][q4 & 3] = pk_bf16(b0, b1); }
;                     lrun = lrun * alpha + ps;
.LBB0_761:
	v_exp_f32_e32 v3, v18
	v_exp_f32_e32 v5, v19
	v_exp_f32_e32 v4, v20
	v_exp_f32_e32 v2, v21
	v_exp_f32_e32 v6, v22
	v_exp_f32_e32 v7, v23
	v_exp_f32_e32 v8, v24
	v_exp_f32_e32 v9, v25
	v_cvt_pk_bf16_f32 v138, v3, v5
	v_cvt_pk_bf16_f32 v139, v4, v2
	v_cvt_pk_bf16_f32 v140, v6, v7
	v_cvt_pk_bf16_f32 v141, v8, v9
	s_and_b64 vcc, exec, s[34:35]
	s_cbranch_vccnz .LBB0_766

; #define LAS __attribute__((address_space(3)))
; __device__ __forceinline__ unsigned pk_bf16(float lo, float hi) { f32x2_t v = {lo, hi}; bf16x2_t b = __builtin_convertvector(v, bf16x2_t); return __builtin_bit_cast(unsigned, b); }
; __device__ __forceinline__ float fexp2(float x) { return __builtin_amdgcn_exp2f(x); }
; #define SBAR __builtin_amdgcn_sched_barrier(0)
; __device__ __forceinline__ void attn_phase(LAS unsigned char* lds, const bf16_t* Q, const bf16_t* Kimg, const bf16_t* Vimg, const bf16_t* Kmeta, const bf16_t* Vmeta,
;                                            bf16_t* O, const float* lamp, const float* sublnw, float lambda_init, int G) {
;     ...
;                     float ps = 0.f;
; #pragma unroll
;                     for (int q4 = 0; q4 < 8; ++q4) {
;                         const float a0 = fexp2(sA[2 * q4]), a1 = fexp2(sA[2 * q4 + 1]), b0 = fexp2(sB[2 * q4]), b1 = fexp2(sB[2 * q4 + 1]);
;                         ps += (a0 + a1) + (b0 + b1);
;                         pk[q4 >> 2][q4 & 3] = pk_bf16(a0, a1); pk[2 + (q4 >> 2)][q4 & 3] = pk_bf16(b0, b1); }
;                     lrun = lrun * alpha + ps;
;                 }
;                 if (skew == 1) { if (j + 3 < NT) WAITV_BAR(4); else WAITV_BAR(0); }
;                 if (active) {
;                     const LAS unsigned char* Vb = lds + 65536 + (j & 3) * 16384;
;                     const LAS unsigned char* Kb = lds + ((j + 1) & 3) * 16384;
;                     bf16x8 fa[4], fb[4];
;     ...
;                     __builtin_amdgcn_s_setprio(1);
;                     VFR(fa, 0);
;                     if (__any(alpha != 1.f)) {
; #pragma unroll
;                         for (int d = 0; d < 4; ++d)
; #pragma unroll
;                             for (int r = 0; r < 16; ++r) o[d][r] *= alpha;
;                     }
;                     SBAR; VFR(fb, 1); SBAR; PVM(fa, 0); SBAR; VFR(fa, 2); SBAR; PVM(fb, 1); SBAR; VFR(fb, 3); SBAR; PVM(fa, 2); SBAR; KFR(fa, 0); SBAR; PVM(fb, 3); SBAR; KFR(fb, 1);
;                     { const int kp0_ = 16 + 64 * j; const float tb_ = slope2 * (float)(kp0_ - qpos0 + 8 * hi) - mrun;
; #pragma unroll
;                       for (int r = 0; r < 16; ++r) { sA[r] = fmaf(slope2, (float)(16 * (r >> 3) + (r & 7)), tb_); sB[r] = fmaf(slope2, (float)(32 + 16 * (r >> 3) + (r & 7)), tb_); } }
;                     SBAR; QKM(fa, 0); SBAR; QKM(fb, 1);
.Latt_noalpha:
	ds_read_b128 v[196:199], v234 offset:4096
	ds_read_b128 v[222:225], v234 offset:4608
	ds_read_b128 v[226:229], v234 offset:5120
	ds_read_b128 v[230:233], v234 offset:5632
	s_waitcnt lgkmcnt(7)
	v_mfma_f32_32x32x16_bf16 v[98:113], v[184:187], v[138:141], v[98:113]
	v_add_f32_e32 v236, v3, v5
	v_add_f32_e32 v237, v4, v2
	v_add_f32_e32 v238, v6, v7
	v_add_f32_e32 v239, v8, v9
	v_exp_f32_e32 v3, v26
	v_exp_f32_e32 v5, v27
	s_waitcnt lgkmcnt(6)
	v_mfma_f32_32x32x16_bf16 v[82:97], v[188:191], v[138:141], v[82:97]
	v_exp_f32_e32 v4, v28
	v_exp_f32_e32 v2, v29
	s_waitcnt lgkmcnt(5)
	v_mfma_f32_32x32x16_bf16 v[66:81], v[202:205], v[138:141], v[66:81]
	v_exp_f32_e32 v6, v30
	v_exp_f32_e32 v7, v31
	s_waitcnt lgkmcnt(4)
	v_mfma_f32_32x32x16_bf16 v[50:65], v[246:249], v[138:141], v[50:65]
	v_exp_f32_e32 v8, v32
	v_exp_f32_e32 v9, v33
	ds_read_b128 v[184:187], v234 offset:8192
	ds_read_b128 v[188:191], v234 offset:8704
	ds_read_b128 v[202:205], v234 offset:9216
	ds_read_b128 v[246:249], v234 offset:9728
	v_cvt_pk_bf16_f32 v142, v3, v5
	v_cvt_pk_bf16_f32 v143, v4, v2
	v_cvt_pk_bf16_f32 v144, v6, v7
	v_cvt_pk_bf16_f32 v145, v8, v9
	v_add_f32_e32 v240, v3, v5
	v_add_f32_e32 v241, v4, v2
	v_add_f32_e32 v242, v6, v7
	v_add_f32_e32 v243, v8, v9
	v_cvt_f32_i32_e32 v193, v179
	v_mov_b32_e32 v177, v176
	s_waitcnt lgkmcnt(7)
	v_mfma_f32_32x32x16_bf16 v[98:113], v[196:199], v[142:145], v[98:113]
	v_exp_f32_e32 v3, v34
	v_exp_f32_e32 v5, v35
	v_fma_f32 v193, v176, v193, -v173
	s_waitcnt lgkmcnt(6)
	v_mfma_f32_32x32x16_bf16 v[82:97], v[222:225], v[142:145], v[82:97]
	v_exp_f32_e32 v4, v36
	v_exp_f32_e32 v2, v37
	v_fma_f32 v18, 0, v176, v193
	v_add_f32_e32 v19, v176, v193
	s_waitcnt lgkmcnt(5)
	v_mfma_f32_32x32x16_bf16 v[66:81], v[226:229], v[142:145], v[66:81]
	v_exp_f32_e32 v6, v38
	v_exp_f32_e32 v7, v39
	v_fmamk_f32 v20, v176, 0x40000000, v193
	v_fmamk_f32 v21, v176, 0x40400000, v193
	s_waitcnt lgkmcnt(4)
	v_mfma_f32_32x32x16_bf16 v[50:65], v[230:233], v[142:145], v[50:65]
	v_exp_f32_e32 v8, v40
	v_exp_f32_e32 v9, v41
	v_fmamk_f32 v22, v176, 0x40800000, v193
	v_fmamk_f32 v23, v176, 0x40a00000, v193
	ds_read_b128 v[196:199], v234 offset:12288
	ds_read_b128 v[222:225], v234 offset:12800
	ds_read_b128 v[226:229], v234 offset:13312
	ds_read_b128 v[230:233], v234 offset:13824
	v_cvt_pk_bf16_f32 v134, v3, v5
	v_cvt_pk_bf16_f32 v135, v4, v2
	v_cvt_pk_bf16_f32 v136, v6, v7
	v_cvt_pk_bf16_f32 v137, v8, v9
	v_add_f32_e32 v11, v3, v5
	v_add_f32_e32 v12, v4, v2
	v_add_f32_e32 v13, v6, v7
	v_add_f32_e32 v192, v8, v9
	s_waitcnt lgkmcnt(7)
	v_mfma_f32_32x32x16_bf16 v[98:113], v[184:187], v[134:137], v[98:113]
	v_exp_f32_e32 v3, v42
	v_exp_f32_e32 v5, v43
	v_add_f32_e32 v236, v11, v236
	v_fmamk_f32 v24, v176, 0x40c00000, v193
	v_fmamk_f32 v25, v176, 0x40e00000, v193
	s_waitcnt lgkmcnt(6)
	v_mfma_f32_32x32x16_bf16 v[82:97], v[188:191], v[134:137], v[82:97]
	v_exp_f32_e32 v4, v44
	v_exp_f32_e32 v2, v45
	v_add_f32_e32 v237, v12, v237
	v_fmamk_f32 v26, v176, 0x41800000, v193
	v_fmamk_f32 v27, v176, 0x41880000, v193
	s_waitcnt lgkmcnt(5)
	v_mfma_f32_32x32x16_bf16 v[66:81], v[202:205], v[134:137], v[66:81]
	v_exp_f32_e32 v6, v46
	v_exp_f32_e32 v7, v47
	v_add_f32_e32 v10, v237, v236
	v_add_f32_e32 v238, v13, v238
	v_fmamk_f32 v28, v176, 0x41900000, v193
	v_fmamk_f32 v29, v176, 0x41980000, v193
	s_waitcnt lgkmcnt(4)
	v_mfma_f32_32x32x16_bf16 v[50:65], v[246:249], v[134:137], v[50:65]
	v_exp_f32_e32 v8, v48
	v_exp_f32_e32 v9, v49
	v_add_f32_e32 v239, v192, v239
	v_add_f32_e32 v10, v238, v10
	v_fmamk_f32 v30, v176, 0x41a00000, v193
	v_fmamk_f32 v31, v176, 0x41a80000, v193
	s_add_i32 s10, s38, 0x8000
	s_and_b32 s10, s10, 0xc000
	v_add_u32_e32 v235, s10, v221
	ds_read_b128 v[184:187], v235
	ds_read_b128 v[188:191], v235 offset:512
	ds_read_b128 v[202:205], v235 offset:2048
	ds_read_b128 v[246:249], v235 offset:2560
	v_cvt_pk_bf16_f32 v146, v3, v5
	v_cvt_pk_bf16_f32 v147, v4, v2
	v_cvt_pk_bf16_f32 v148, v6, v7
	v_cvt_pk_bf16_f32 v149, v8, v9
	v_add_f32_e32 v11, v3, v5
	v_add_f32_e32 v12, v4, v2
	v_add_f32_e32 v13, v6, v7
	v_add_f32_e32 v192, v8, v9
	v_add_f32_e32 v10, v239, v10
	s_waitcnt lgkmcnt(7)
	v_mfma_f32_32x32x16_bf16 v[98:113], v[196:199], v[146:149], v[98:113]
	v_add_f32_e32 v240, v11, v240
	v_add_f32_e32 v10, v240, v10
	v_fmamk_f32 v34, v176, 0x42000000, v193
	v_fmamk_f32 v35, v176, 0x42040000, v193
	v_fmamk_f32 v36, v176, 0x42080000, v193
	v_fmamk_f32 v37, v176, 0x420c0000, v193
	s_waitcnt lgkmcnt(6)
	v_mfma_f32_32x32x16_bf16 v[82:97], v[222:225], v[146:149], v[82:97]
	v_add_f32_e32 v241, v12, v241
	v_add_f32_e32 v10, v241, v10
	v_fmamk_f32 v38, v176, 0x42100000, v193
	v_fmamk_f32 v39, v176, 0x42140000, v193
	v_fmamk_f32 v40, v176, 0x42180000, v193
	v_fmamk_f32 v41, v176, 0x421c0000, v193
	s_waitcnt lgkmcnt(5)
	v_mfma_f32_32x32x16_bf16 v[66:81], v[226:229], v[146:149], v[66:81]
	v_add_f32_e32 v242, v13, v242
	v_add_f32_e32 v10, v242, v10
	v_fmamk_f32 v42, v176, 0x42400000, v193
	v_fmamk_f32 v43, v176, 0x42440000, v193
	v_fmamk_f32 v44, v176, 0x42480000, v193
	v_fmamk_f32 v45, v176, 0x424c0000, v193
	s_waitcnt lgkmcnt(4)
	v_mfma_f32_32x32x16_bf16 v[50:65], v[230:233], v[146:149], v[50:65]
	v_add_f32_e32 v243, v192, v243
	v_add_f32_e32 v10, v243, v10
	v_fmamk_f32 v46, v176, 0x42500000, v193
	v_fmamk_f32 v47, v176, 0x42540000, v193
	v_fmamk_f32 v48, v176, 0x42580000, v193
	v_fmamk_f32 v49, v176, 0x425c0000, v193
	v_fma_f32 v17, v17, v178, v10
	v_fmamk_f32 v32, v176, 0x41b00000, v193
	v_fmamk_f32 v33, v176, 0x41b80000, v193
	ds_read_b128 v[196:199], v235 offset:4096
	ds_read_b128 v[222:225], v235 offset:4608
	ds_read_b128 v[226:229], v235 offset:6144
	ds_read_b128 v[230:233], v235 offset:6656
	s_waitcnt lgkmcnt(7)
	v_mfma_f32_32x32x16_bf16 v[18:33], v[184:187], v[118:121], v[18:33]
	s_waitcnt lgkmcnt(6)
	v_mfma_f32_32x32x16_bf16 v[34:49], v[188:191], v[118:121], v[34:49]
	s_waitcnt lgkmcnt(5)
	v_mfma_f32_32x32x16_bf16 v[18:33], v[202:205], v[122:125], v[18:33]
	s_waitcnt lgkmcnt(4)
	v_mfma_f32_32x32x16_bf16 v[34:49], v[246:249], v[122:125], v[34:49]
	s_waitcnt lgkmcnt(3)
	v_mfma_f32_32x32x16_bf16 v[18:33], v[196:199], v[126:129], v[18:33]
	s_waitcnt lgkmcnt(2)
	v_mfma_f32_32x32x16_bf16 v[34:49], v[222:225], v[126:129], v[34:49]
	s_waitcnt lgkmcnt(1)
	v_mfma_f32_32x32x16_bf16 v[18:33], v[226:229], v[130:133], v[18:33]
	s_waitcnt lgkmcnt(0)
	v_mfma_f32_32x32x16_bf16 v[34:49], v[230:233], v[130:133], v[34:49]
	s_setprio 0
